# phase-0 adaLN weight rows loaded with the non-temporal hint (read once)
# speedup vs baseline: 1.0055x; 1.0055x over previous
; __device__ __forceinline__ void p0_adaln(const Params& P, float* lf) {
;     ...
;     for (int item = blockIdx.x; item < 768; item += gridDim.x) {
;         const int l = item / 192, j0 = (item % 192) * 32;
;         const int col = lane & 31, kh = lane >> 5;
;         const float* w = ada_w + (size_t)l * 1024 * 6144 + j0 + col;
;         float acc[17];
; #pragma unroll
;         for (int r = 0; r < 17; ++r) acc[r] = 0.f;
;         const int kb = wave * 128 + kh * 64;
;         for (int k0 = kb; k0 < kb + 64; k0 += 8) {
;             float wv[8];
; #pragma unroll
;             for (int e = 0; e < 8; ++e) wv[e] = w[(size_t)(k0 + e) * 6144];
.LBB0_27:
	s_mul_hi_i32 s4, s26, 0x2aaaaaab
	s_lshr_b32 s5, s4, 31
	s_ashr_i32 s27, s4, 5
	s_add_i32 s27, s27, s5
	s_mul_i32 s4, s27, 0xc0
	s_sub_i32 s4, s26, s4
	s_lshl_b32 s8, s4, 5
	s_ashr_i32 s9, s8, 31
	s_mul_i32 s13, s27, 0x1800000
	s_lshl_b64 s[4:5], s[8:9], 2
	s_mul_hi_i32 s12, s27, 0x1800000
	s_add_u32 s4, s13, s4
	s_addc_u32 s5, s12, s5
	v_lshl_add_u64 v[138:139], v[136:137], 0, s[4:5]
	s_mov_b64 s[12:13], 0
	v_mov_b32_e32 v174, v172
	v_mov_b32_e32 v175, v171
	v_mov_b32_e32 v146, 0
	v_mov_b32_e32 v147, v133
	v_mov_b32_e32 v140, 0
	v_mov_b32_e32 v141, v133
	v_mov_b32_e32 v142, 0
	v_mov_b32_e32 v143, v133
	v_mov_b32_e32 v144, 0
	v_mov_b32_e32 v145, v133
	v_mov_b32_e32 v148, 0
	v_mov_b32_e32 v149, v133
	v_mov_b32_e32 v150, 0
	v_mov_b32_e32 v151, v133
	v_mov_b32_e32 v152, 0
	v_mov_b32_e32 v153, v133
	v_mov_b32_e32 v154, 0
	v_mov_b32_e32 v155, v133
	v_mov_b32_e32 v176, 0
	s_mov_b32 s98, 0xfffd6000
	s_mov_b32 s99, -1
	v_lshl_add_u64 v[248:249], v[138:139], 0, s[98:99]
	global_load_dword v180, v[248:249], off nt
	s_mov_b64 s[98:99], 0x6000
	v_lshl_add_u64 v[242:243], v[248:249], 0, s[98:99]
	global_load_dword v181, v[242:243], off nt
	s_mov_b64 s[98:99], 0xc000
	v_lshl_add_u64 v[244:245], v[248:249], 0, s[98:99]
	global_load_dword v182, v[244:245], off nt
	s_mov_b64 s[98:99], 0x12000
	v_lshl_add_u64 v[246:247], v[248:249], 0, s[98:99]
	global_load_dword v183, v[246:247], off nt
	s_mov_b64 s[98:99], 0x18000
	v_lshl_add_u64 v[240:241], v[248:249], 0, s[98:99]
	global_load_dword v164, v[240:241], off nt
	s_mov_b64 s[98:99], 0x1e000
	v_lshl_add_u64 v[242:243], v[248:249], 0, s[98:99]
	global_load_dword v165, v[242:243], off nt
	s_mov_b64 s[98:99], 0x24000
	v_lshl_add_u64 v[244:245], v[248:249], 0, s[98:99]
	global_load_dword v166, v[244:245], off nt
	s_mov_b64 s[98:99], 0x2a000
	v_lshl_add_u64 v[246:247], v[248:249], 0, s[98:99]
	global_load_dword v132, v[246:247], off nt
	s_mov_b64 s[98:99], 0x30000
	v_lshl_add_u64 v[240:241], v[248:249], 0, s[98:99]
	global_load_dword v184, v[240:241], off nt
	s_mov_b64 s[98:99], 0x36000
	v_lshl_add_u64 v[242:243], v[248:249], 0, s[98:99]
	global_load_dword v185, v[242:243], off nt
	s_mov_b64 s[98:99], 0x3c000
	v_lshl_add_u64 v[244:245], v[248:249], 0, s[98:99]
	global_load_dword v186, v[244:245], off nt
	s_mov_b64 s[98:99], 0x42000
	v_lshl_add_u64 v[246:247], v[248:249], 0, s[98:99]
	global_load_dword v187, v[246:247], off nt
	s_mov_b64 s[98:99], 0x48000
	v_lshl_add_u64 v[240:241], v[248:249], 0, s[98:99]
	global_load_dword v188, v[240:241], off nt
	s_mov_b64 s[98:99], 0x4e000
	v_lshl_add_u64 v[242:243], v[248:249], 0, s[98:99]
	global_load_dword v189, v[242:243], off nt
	s_mov_b64 s[98:99], 0x54000
	v_lshl_add_u64 v[244:245], v[248:249], 0, s[98:99]
	global_load_dword v190, v[244:245], off nt
	s_mov_b64 s[98:99], 0x5a000
	v_lshl_add_u64 v[246:247], v[248:249], 0, s[98:99]
	global_load_dword v191, v[246:247], off nt
	s_mov_b64 s[98:99], 0x60000
	v_lshl_add_u64 v[240:241], v[248:249], 0, s[98:99]
	global_load_dword v192, v[240:241], off nt
	s_mov_b64 s[98:99], 0x66000
	v_lshl_add_u64 v[242:243], v[248:249], 0, s[98:99]
	global_load_dword v193, v[242:243], off nt
	s_mov_b64 s[98:99], 0x6c000
	v_lshl_add_u64 v[244:245], v[248:249], 0, s[98:99]
	global_load_dword v194, v[244:245], off nt
	s_mov_b64 s[98:99], 0x72000
	v_lshl_add_u64 v[246:247], v[248:249], 0, s[98:99]
	global_load_dword v195, v[246:247], off nt
	s_mov_b64 s[98:99], 0x78000
	v_lshl_add_u64 v[240:241], v[248:249], 0, s[98:99]
	global_load_dword v196, v[240:241], off nt
	s_mov_b64 s[98:99], 0x7e000
	v_lshl_add_u64 v[242:243], v[248:249], 0, s[98:99]
	global_load_dword v197, v[242:243], off nt
	s_mov_b64 s[98:99], 0x84000
	v_lshl_add_u64 v[244:245], v[248:249], 0, s[98:99]
	global_load_dword v198, v[244:245], off nt
	s_mov_b64 s[98:99], 0x8a000
	v_lshl_add_u64 v[246:247], v[248:249], 0, s[98:99]
	global_load_dword v199, v[246:247], off nt
	s_mov_b64 s[98:99], 0x90000
	v_lshl_add_u64 v[240:241], v[248:249], 0, s[98:99]
	global_load_dword v200, v[240:241], off nt
	s_mov_b64 s[98:99], 0x96000
	v_lshl_add_u64 v[242:243], v[248:249], 0, s[98:99]
	global_load_dword v201, v[242:243], off nt
	s_mov_b64 s[98:99], 0x9c000
	v_lshl_add_u64 v[244:245], v[248:249], 0, s[98:99]
	global_load_dword v202, v[244:245], off nt
	s_mov_b64 s[98:99], 0xa2000
	v_lshl_add_u64 v[246:247], v[248:249], 0, s[98:99]
	global_load_dword v203, v[246:247], off nt
	s_mov_b64 s[98:99], 0xa8000
	v_lshl_add_u64 v[240:241], v[248:249], 0, s[98:99]
; __device__ __forceinline__ void p0_adaln(const Params& P, float* lf) {
;     ...
;         for (int k0 = kb; k0 < kb + 64; k0 += 8) {
;             float wv[8];
; #pragma unroll
;             for (int e = 0; e < 8; ++e) wv[e] = w[(size_t)(k0 + e) * 6144];
	global_load_dword v204, v[240:241], off nt
	s_mov_b64 s[98:99], 0xae000
	v_lshl_add_u64 v[242:243], v[248:249], 0, s[98:99]
	global_load_dword v205, v[242:243], off nt
	s_mov_b64 s[98:99], 0xb4000
	v_lshl_add_u64 v[244:245], v[248:249], 0, s[98:99]
	global_load_dword v206, v[244:245], off nt
	s_mov_b64 s[98:99], 0xba000
	v_lshl_add_u64 v[246:247], v[248:249], 0, s[98:99]
	global_load_dword v207, v[246:247], off nt
	s_mov_b64 s[98:99], 0xc0000
	v_lshl_add_u64 v[240:241], v[248:249], 0, s[98:99]
	global_load_dword v208, v[240:241], off nt
	s_mov_b64 s[98:99], 0xc6000
	v_lshl_add_u64 v[242:243], v[248:249], 0, s[98:99]
	global_load_dword v209, v[242:243], off nt
	s_mov_b64 s[98:99], 0xcc000
	v_lshl_add_u64 v[244:245], v[248:249], 0, s[98:99]
	global_load_dword v210, v[244:245], off nt
	s_mov_b64 s[98:99], 0xd2000
	v_lshl_add_u64 v[246:247], v[248:249], 0, s[98:99]
	global_load_dword v211, v[246:247], off nt
	s_mov_b64 s[98:99], 0xd8000
	v_lshl_add_u64 v[240:241], v[248:249], 0, s[98:99]
	global_load_dword v212, v[240:241], off nt
	s_mov_b64 s[98:99], 0xde000
	v_lshl_add_u64 v[242:243], v[248:249], 0, s[98:99]
	global_load_dword v213, v[242:243], off nt
	s_mov_b64 s[98:99], 0xe4000
	v_lshl_add_u64 v[244:245], v[248:249], 0, s[98:99]
	global_load_dword v214, v[244:245], off nt
	s_mov_b64 s[98:99], 0xea000
	v_lshl_add_u64 v[246:247], v[248:249], 0, s[98:99]
	global_load_dword v215, v[246:247], off nt
	s_mov_b64 s[98:99], 0xf0000
	v_lshl_add_u64 v[240:241], v[248:249], 0, s[98:99]
	global_load_dword v216, v[240:241], off nt
	s_mov_b64 s[98:99], 0xf6000
	v_lshl_add_u64 v[242:243], v[248:249], 0, s[98:99]
	global_load_dword v217, v[242:243], off nt
	s_mov_b64 s[98:99], 0xfc000
	v_lshl_add_u64 v[244:245], v[248:249], 0, s[98:99]
	global_load_dword v218, v[244:245], off nt
	s_mov_b64 s[98:99], 0x102000
	v_lshl_add_u64 v[246:247], v[248:249], 0, s[98:99]
	global_load_dword v219, v[246:247], off nt
	s_mov_b64 s[98:99], 0x108000
	v_lshl_add_u64 v[240:241], v[248:249], 0, s[98:99]
	global_load_dword v220, v[240:241], off nt
	s_mov_b64 s[98:99], 0x10e000
	v_lshl_add_u64 v[242:243], v[248:249], 0, s[98:99]
	global_load_dword v221, v[242:243], off nt
	s_mov_b64 s[98:99], 0x114000
	v_lshl_add_u64 v[244:245], v[248:249], 0, s[98:99]
	global_load_dword v222, v[244:245], off nt
	s_mov_b64 s[98:99], 0x11a000
	v_lshl_add_u64 v[246:247], v[248:249], 0, s[98:99]
	global_load_dword v223, v[246:247], off nt
	s_mov_b64 s[98:99], 0x120000
	v_lshl_add_u64 v[240:241], v[248:249], 0, s[98:99]
	global_load_dword v224, v[240:241], off nt
	s_mov_b64 s[98:99], 0x126000
	v_lshl_add_u64 v[242:243], v[248:249], 0, s[98:99]
	global_load_dword v225, v[242:243], off nt
	s_mov_b64 s[98:99], 0x12c000
	v_lshl_add_u64 v[244:245], v[248:249], 0, s[98:99]
	global_load_dword v226, v[244:245], off nt
	s_mov_b64 s[98:99], 0x132000
	v_lshl_add_u64 v[246:247], v[248:249], 0, s[98:99]
	global_load_dword v227, v[246:247], off nt
	s_mov_b64 s[98:99], 0x138000
	v_lshl_add_u64 v[240:241], v[248:249], 0, s[98:99]
	global_load_dword v228, v[240:241], off nt
	s_mov_b64 s[98:99], 0x13e000
	v_lshl_add_u64 v[242:243], v[248:249], 0, s[98:99]
	global_load_dword v229, v[242:243], off nt
	s_mov_b64 s[98:99], 0x144000
	v_lshl_add_u64 v[244:245], v[248:249], 0, s[98:99]
	global_load_dword v230, v[244:245], off nt
	s_mov_b64 s[98:99], 0x14a000
	v_lshl_add_u64 v[246:247], v[248:249], 0, s[98:99]
	global_load_dword v231, v[246:247], off nt
	s_mov_b64 s[98:99], 0x150000
	v_lshl_add_u64 v[240:241], v[248:249], 0, s[98:99]
	global_load_dword v232, v[240:241], off nt
	s_mov_b64 s[98:99], 0x156000
	v_lshl_add_u64 v[242:243], v[248:249], 0, s[98:99]
	global_load_dword v233, v[242:243], off nt
	s_mov_b64 s[98:99], 0x15c000
	v_lshl_add_u64 v[244:245], v[248:249], 0, s[98:99]
	global_load_dword v234, v[244:245], off nt
	s_mov_b64 s[98:99], 0x162000
	v_lshl_add_u64 v[246:247], v[248:249], 0, s[98:99]
	global_load_dword v235, v[246:247], off nt
	s_mov_b64 s[98:99], 0x168000
	v_lshl_add_u64 v[240:241], v[248:249], 0, s[98:99]
	global_load_dword v236, v[240:241], off nt
	s_mov_b64 s[98:99], 0x16e000
	v_lshl_add_u64 v[242:243], v[248:249], 0, s[98:99]
	global_load_dword v237, v[242:243], off nt
	s_mov_b64 s[98:99], 0x174000
	v_lshl_add_u64 v[244:245], v[248:249], 0, s[98:99]
	global_load_dword v238, v[244:245], off nt
	s_mov_b64 s[98:99], 0x17a000
	v_lshl_add_u64 v[246:247], v[248:249], 0, s[98:99]
	global_load_dword v239, v[246:247], off nt
